# in-projection-1 half tiles: half-tile index permuted so each workgroup's 128-row half tile belongs to an M-tile owned by its XCD
# baseline (speedup 1.0000x reference)
;   DI bf16_t* wt_in1() const { return (bf16_t*)(ws + OFF_WT_IN1); }
;   DI bf16_t* h() const { return (bf16_t*)(ws + OFF_H); }
;   DI bf16_t* z() const { return (bf16_t*)(ws + OFF_Z); }
; DI int otid() { int t = threadIdx.x; asm volatile("" : "+v"(t)); return t; }
; DI void gemm_half_rowbf16(const bf16_t* __restrict__ A, int lda, const bf16_t* __restrict__ Bt, int ldb, int K, int m0, int n0, char* smem, bf16_t* __restrict__ Out, int ldo) {
;   bf16_t* lds = (bf16_t*)smem;
;   const int tid = otid(), lane = tid & 63, w = __builtin_amdgcn_readfirstlane(tid >> 6), l32 = lane & 31, g = lane >> 5;
;   f32x16 acc[4];
; #pragma unroll
;   for (int b = 0; b < 4; ++b)
; #pragma unroll
;     for (int r = 0; r < 16; ++r) acc[b][r] = 0.f;
;   const int lrow = tid >> 3, kc = tid & 7;
;   const unsigned aoff = (unsigned)(lrow * lda + kc * 8) * 2u, boff = (unsigned)(lrow * ldb + kc * 8) * 2u;
;   const char* ag = (const char*)(A + (size_t)m0 * lda);
;   const char* bg = (const char*)(Bt + (size_t)n0 * ldb);
; DI void phase_gemm_in1(const Params& p, char* smem) {
;     ...
;   for (int t = blockIdx.x; t < 256; t += gridDim.x) gemm_half_rowbf16(p.h(), D, p.wt_in1(), D, D, (t & 127) * 128, (23 + (t >> 7)) * 256, smem, p.z(), LDZ1);
.LBB0_913:
	s_cmpk_gt_i32 s84, 0xff
	s_cbranch_scc1 .LBB0_916
	s_add_u32 s16, s22, 0x40c0000
	s_addc_u32 s17, s23, 0
	s_add_u32 s18, s22, 0x1980000
	s_addc_u32 s19, s23, 0
	s_add_u32 s0, s22, 0x80c0000
	s_addc_u32 s1, s23, 0
	s_lshl_b32 s24, s96, 1
	s_mov_b32 s98, s84
	s_cmp_lg_u32 s96, 0x100
	s_cbranch_scc1 .Lhx_skip
	s_and_b32 s98, s84, 0xf0
	s_and_b32 s99, s84, 7
	s_lshl_b32 s99, s99, 1
	s_or_b32 s98, s98, s99
	s_bfe_u32 s99, s84, 0x10003
	s_or_b32 s98, s98, s99
.Lhx_skip:
	s_lshl_b32 s25, s98, 7
	s_lshl_b32 s27, s96, 7
	v_mov_b32_e32 v65, 0
	s_mov_b32 s28, 0x40000
	s_mov_b32 s29, 0x80000
	s_mov_b32 s30, 0xc0000
	s_movk_i32 s31, 0x90
	s_movk_i32 s33, 0xffe0
	s_add_i32 s34, 16, 0x1b000
	s_add_i32 s35, 16, 0x12000
	s_mov_b64 s[2:3], 0x66000
	s_mov_b64 s[6:7], 0xcc000
	s_mov_b64 s[8:9], 0x132000
	s_mov_b32 s36, s84
	v_readlane_b32 s4, v252, 36
